# E10 + mixer C loop staggered by half a step: waves 4-7 barrier between QK and PV halves, running half a step ahead of waves 0-3
# baseline (speedup 1.0000x reference)
; #define WAIT_BAR(N) asm volatile("s_waitcnt vmcnt(" #N ") lgkmcnt(0)\n\ts_barrier" ::: "memory")
;   #define DMA_K(t, slot) glds16(ksrc + (long)(t) * KVBLK * PQ, (unsigned)__builtin_amdgcn_readfirstlane(kdst + (slot)))
; template <int THRL> __device__ __forceinline__ void attn_unit(const int tid, const float mfix, int q0, int NT, const bf16* Qh, const bf16* __restrict__ Kh, const bf16* __restrict__ Vh, const bf16* Zh, bf16* Oh, const long PQ, const long PO, char* shm) {
;   const int lane = tid & 63, r32 = lane & 31, hi = lane >> 5; const int wid = __builtin_amdgcn_readfirstlane(tid >> 6);
;   const bf16* Qw = Qh + (long)(q0 + wid * QBLK) * PQ;
;   const unsigned lds0 = (unsigned)(uintptr_t)shm;
;   float* wsf = (float*)(shm + LDS_WS) + wid * 64;
;   const bf16* ksrc = Kh + (long)lane * PQ + wid * 8;
;   const bf16* vsrc = Vh + (long)(16 * (wid & 3) + (lane >> 2)) * PQ + (wid >> 2) * 32 + (lane & 3) * 8;
;   const unsigned kdst = lds0 + LDS_K + wid * 1024, vdst = lds0 + LDS_V + wid * 1024;
;     ...
;   const int vb0 = (int)(lds0 + LDS_V) + ((lane >> 4) & 1) * 32 + (lane & 3) * 8 + (4 * hi + ((lane & 15) >> 2)) * 64;
;   const char* Kbase = shm + LDS_K; bf16x8 kf[8];
;   const lds_cptr shm3 = (lds_cptr)shm; const lds_cptr kp0 = shm3 + LDS_K + hi * 1024 + r32 * 16; const lds_cptr vp0 = shm3 + LDS_V + ((lane >> 4) & 1) * 32 + (lane & 3) * 8 + (4 * hi + ((lane & 15) >> 2)) * 64;
;   DMA_K(0, 0); DMA_V(0, 0); DMA_K(1, SLOTB);
;   bf16x8 qr[4];
;   #pragma unroll
;   for (int d0 = 0; d0 < 4; ++d0) qr[d0] = *reinterpret_cast<const bf16x8*>(&Qw[(long)r32 * PQ + d0 * 16 + hi * 8]);
;   float zf_; asm volatile("v_mov_b32 %0, 0" : "=v"(zf_)); f32x16 zv_;
;   #pragma unroll
;   for (int r = 0; r < 16; ++r) zv_[r] = zf_;
;   float l_reg = 0.f; f32x16 o[2]; o[0] = zv_; o[1] = zv_; f32x16 negm;
;   #pragma unroll
;   for (int r = 0; r < 16; ++r) negm[r] = -mfix;
;   asm volatile("" : "+v"(negm));
;     ...
;   f32x16 pA0, pA1, pB0, pB1;
;   int sl_prev = 0, sl_cur = 0, sl_next = SLOTB;
;     ...
;   DMA_K(2, 2 * SLOTB);
;   WAIT_BAR(3);
;   qkt(pA0, pA1, Kbase, qr, negm, r32, hi); asm volatile("s_nop 15\n\ts_nop 7" : "+v"(pA0), "+v"(pA1));
;   START(pA0, pA1);
;   _Pragma("unroll") for (int r = 0; r < 16; ++r) pA1[r] = __builtin_amdgcn_exp2f(pA1[r]);
;   WAIT_BAR(0);
;   DMA_K(3, 0); DMA_V(1, SLOTB);
;   ROT();
;   kload8(kf, kp0 + sl_cur);
;   WAIT_BAR(2);
.LBB0_387:
	s_or_b32 s1, s1, s0
	v_readfirstlane_b32 s20, v238
	s_xor_b64 s[8:9], s[10:11], -1
	s_lshl_b32 s10, s1, 8
	s_ashr_i32 s1, s20, 6
	s_lshr_b32 s98, s1, 2
	s_nop 0
	s_lshl_b32 s16, s1, 4
	v_and_or_b32 v16, s16, 48, v240
	s_ashr_i32 s16, s20, 3
	s_lshl_b32 s11, s1, 5
	s_lshl_b32 s14, s1, 3
	s_andn2_b32 s16, s16, 31
	s_add_i32 s10, s11, s10
	s_ashr_i32 s15, s14, 31
	s_ashr_i32 s17, s16, 31
	s_ashr_i32 s11, s10, 31
	s_lshl_b64 s[14:15], s[14:15], 1
	v_mul_u32_u24_e32 v16, 0x1a40, v16
	s_lshl_b64 s[16:17], s[16:17], 1
	s_lshl_b32 s19, s1, 10
	v_lshlrev_b32_e32 v188, 1, v16
	s_cmp_lg_u32 0, -1
	v_lshl_add_u64 v[16:17], s[6:7], 0, v[188:189]
	s_cselect_b32 s18, 0, 0
	v_lshl_add_u64 v[222:223], v[190:191], 0, s[14:15]
	v_lshl_add_u64 v[16:17], v[16:17], 0, s[16:17]
	v_mov_b32_e32 v219, v189
	s_add_i32 s19, s19, s18
	s_mov_b32 s21, m0
	s_mov_b32 m0, s19
	s_nop 0
	global_load_lds_dwordx4 v[222:223], off
	s_mov_b32 m0, s21
	s_mul_hi_i32 s13, s10, 0x1a40
	s_mul_i32 s12, s10, 0x1a40
	v_lshl_add_u64 v[220:221], v[16:17], 0, v[218:219]
	s_add_i32 s18, s19, 0x6000
	s_mov_b32 s21, m0
	s_mov_b32 m0, s18
	s_nop 0
	global_load_lds_dwordx4 v[220:221], off
	s_mov_b32 m0, s21
	v_lshl_add_u64 v[16:17], v[222:223], 0, s[86:87]
	s_add_i32 s21, s19, 0x2000
	s_mov_b32 s22, m0
	s_mov_b32 m0, s21
	s_nop 0
	global_load_lds_dwordx4 v[16:17], off
	s_mov_b32 m0, s22
	v_lshl_add_u64 v[16:17], s[12:13], 1, v[192:193]
	global_load_dwordx4 v[172:175], v[16:17], off
	global_load_dwordx4 v[168:171], v[16:17], off offset:32
	global_load_dwordx4 v[164:167], v[16:17], off offset:64
	global_load_dwordx4 v[152:155], v[16:17], off offset:96
	v_mov_b64_e32 v[62:63], v[14:15]
	v_mov_b64_e32 v[60:61], v[12:13]
	v_mov_b64_e32 v[58:59], v[10:11]
	v_mov_b64_e32 v[56:57], v[8:9]
	v_mov_b64_e32 v[54:55], v[6:7]
	v_mov_b64_e32 v[52:53], v[4:5]
	v_mov_b64_e32 v[50:51], v[2:3]
	v_mov_b64_e32 v[48:49], v[0:1]
	v_lshl_add_u64 v[18:19], v[222:223], 0, s[88:89]
	s_add_i32 s21, s19, 0x4000
	v_mov_b32 v16, 0
	s_mov_b32 s22, m0
	s_mov_b32 m0, s21
	s_nop 0
	global_load_lds_dwordx4 v[18:19], off
	s_mov_b32 m0, s22
	s_waitcnt vmcnt(3) lgkmcnt(0)
	s_barrier
	ds_read_b128 v[18:21], v242
	ds_read_b128 v[40:43], v242 offset:512
	v_lshl_add_u64 v[224:225], v[214:215], 0, s[14:15]
	s_add_i32 s14, s19, 0x8000
	v_lshl_add_u64 v[22:23], s[16:17], 0, v[188:189]
	s_mov_b32 s21, -1
	s_movk_i32 s22, 0x2000
	s_movk_i32 s23, 0x4000
	v_mov_b32_e32 v219, 0
	s_mov_b32 s24, 0
	v_lshl_add_u64 v[226:227], v[216:217], 0, v[22:23]
	v_mov_b32_e32 v17, v16
	v_mov_b32_e32 v22, v16
	v_mov_b32_e32 v23, v16
	s_waitcnt vmcnt(3) lgkmcnt(1)
	v_mfma_f32_32x32x16_bf16 v[64:79], v[18:21], v[172:175], v[48:63]
	s_waitcnt lgkmcnt(0)
	v_mfma_f32_32x32x16_bf16 v[24:39], v[40:43], v[172:175], v[48:63]
	ds_read_b128 v[18:21], v242 offset:2048
	ds_read_b128 v[40:43], v242 offset:2560
	s_waitcnt vmcnt(2) lgkmcnt(1)
	v_mfma_f32_32x32x16_bf16 v[64:79], v[18:21], v[168:171], v[64:79]
	s_waitcnt lgkmcnt(0)
	v_mfma_f32_32x32x16_bf16 v[24:39], v[40:43], v[168:171], v[24:39]
	ds_read_b128 v[18:21], v242 offset:4096
	ds_read_b128 v[40:43], v242 offset:4608
	s_waitcnt vmcnt(1) lgkmcnt(1)
	v_mfma_f32_32x32x16_bf16 v[64:79], v[18:21], v[164:167], v[64:79]
	ds_read_b128 v[44:47], v242 offset:6656
	ds_read_b128 v[18:21], v242 offset:6144
	s_waitcnt lgkmcnt(2)
	v_mfma_f32_32x32x16_bf16 v[24:39], v[40:43], v[164:167], v[24:39]
	v_lshl_add_u64 v[40:41], v[222:223], 0, s[90:91]
	v_lshl_add_u64 v[42:43], v[220:221], 0, s[86:87]
	s_waitcnt vmcnt(0) lgkmcnt(0)
	v_mfma_f32_32x32x16_bf16 v[64:79], v[18:21], v[152:155], v[64:79]
	v_mov_b32_e32 v18, v16
	v_mov_b32_e32 v19, v16
	v_mov_b32_e32 v20, v16
	v_mov_b32_e32 v21, v16
	v_mfma_f32_32x32x16_bf16 v[24:39], v[44:47], v[152:155], v[24:39]
	s_nop 15
	s_nop 7
	s_waitcnt vmcnt(0) lgkmcnt(0)
	s_barrier
	s_mov_b32 s15, m0
	s_mov_b32 m0, s19
	s_nop 0
	global_load_lds_dwordx4 v[40:41], off
	s_mov_b32 m0, s15
	v_mov_b32_e32 v40, v16
	s_mov_b32 s15, m0
	s_mov_b32 m0, s14
	s_nop 0
	global_load_lds_dwordx4 v[42:43], off
	s_mov_b32 m0, s15
	ds_read_b128 v[96:99], v242 offset:8192
	ds_read_b128 v[180:183], v242 offset:8704
	ds_read_b128 v[184:187], v242 offset:10240
	ds_read_b128 v[176:179], v242 offset:10752
	ds_read_b128 v[140:143], v242 offset:12288
	ds_read_b128 v[136:139], v242 offset:12800
	ds_read_b128 v[132:135], v242 offset:14336
	ds_read_b128 v[128:131], v242 offset:14848
	v_exp_f32_e32 v80, v64
	v_exp_f32_e32 v81, v65
	v_exp_f32_e32 v82, v66
	v_exp_f32_e32 v83, v67
	v_exp_f32_e32 v84, v68
	v_exp_f32_e32 v85, v69
	v_exp_f32_e32 v86, v70
	v_exp_f32_e32 v87, v71
	v_exp_f32_e32 v88, v72
	v_exp_f32_e32 v89, v73
	v_exp_f32_e32 v90, v74
	v_exp_f32_e32 v91, v75
	v_exp_f32_e32 v92, v76
	v_exp_f32_e32 v93, v77
	v_exp_f32_e32 v94, v78
	v_exp_f32_e32 v95, v79
	v_exp_f32_e32 v64, v24
	v_exp_f32_e32 v65, v25
	v_exp_f32_e32 v66, v26
	v_exp_f32_e32 v67, v27
	v_exp_f32_e32 v68, v28
	v_exp_f32_e32 v69, v29
	v_exp_f32_e32 v70, v30
	v_exp_f32_e32 v71, v31
	v_exp_f32_e32 v72, v32
	v_exp_f32_e32 v73, v33
	v_exp_f32_e32 v74, v34
	v_exp_f32_e32 v75, v35
	v_exp_f32_e32 v76, v36
	v_exp_f32_e32 v77, v37
	v_exp_f32_e32 v78, v38
	v_exp_f32_e32 v79, v39
	s_waitcnt vmcnt(0) lgkmcnt(0)
	s_barrier
	v_mov_b32_e32 v24, v16
	v_mov_b32_e32 v25, v16
	v_mov_b32_e32 v26, v16
	v_mov_b32_e32 v27, v16
	v_mov_b32_e32 v28, v16
	v_mov_b32_e32 v29, v16
	v_mov_b32_e32 v30, v16
	v_mov_b32_e32 v31, v16
	v_mov_b32_e32 v32, v16
	v_mov_b32_e32 v33, v16
	v_mov_b32_e32 v34, v16
	v_mov_b32_e32 v35, v16
	v_mov_b32_e32 v36, v16
	v_mov_b32_e32 v37, v16
	v_mov_b32_e32 v38, v16
	v_mov_b32_e32 v39, v16
	v_mov_b32_e32 v41, v16
	v_mov_b32_e32 v42, v16
	v_mov_b32_e32 v43, v16
	v_mov_b32_e32 v44, v16
	v_mov_b32_e32 v45, v16
	v_mov_b32_e32 v46, v16
	v_mov_b32_e32 v47, v16
; #define WAIT_BAR(N) asm volatile("s_waitcnt vmcnt(" #N ") lgkmcnt(0)\n\ts_barrier" ::: "memory")
;   #define RESC() do { } while (0)
;   #define ROT() do { sl_prev = sl_cur; sl_cur = sl_next; sl_next = (sl_next == (NSLOT - 1) * SLOTB) ? 0 : sl_next + SLOTB; } while (0)
; template <int THRL> __device__ __forceinline__ void attn_unit(const int tid, const float mfix, int q0, int NT, const bf16* Qh, const bf16* __restrict__ Kh, const bf16* __restrict__ Vh, const bf16* Zh, bf16* Oh, const long PQ, const long PO, char* shm) {
;     ...
;   int t = 1;
;   for (; t + 5 < NT; t += 2) {
;     STEP(pB0, pB1, pA0, pA1, t, true, true, true);     WAIT_BAR(2); RESC(); ROT();
.LBB0_388:
	s_mov_b32 s14, s23
	s_mov_b32 s15, s22
	v_add_u32_e32 v188, s24, v244
	ds_read_b64_tr_b16 v[234:235], v188 offset:24576
	ds_read_b64_tr_b16 v[236:237], v188 offset:25088
	v_add_f32_e32 v100, v80, v81
	v_add_f32_e32 v100, v82, v100
	v_add_f32_e32 v100, v83, v100
	v_add_f32_e32 v100, v84, v100
	v_add_f32_e32 v100, v85, v100
	v_cvt_pk_bf16_f32 v160, v80, v81
	v_cvt_pk_bf16_f32 v161, v82, v83
	s_waitcnt lgkmcnt(9)
	v_mfma_f32_32x32x16_bf16 v[112:127], v[96:99], v[172:175], v[48:63]
	ds_read_b64_tr_b16 v[80:81], v188 offset:28672
	ds_read_b64_tr_b16 v[82:83], v188 offset:29184
	v_add_f32_e32 v96, v86, v100
	v_add_f32_e32 v96, v87, v96
	v_add_f32_e32 v96, v88, v96
	v_add_f32_e32 v144, v89, v96
	s_waitcnt lgkmcnt(10)
	v_mfma_f32_32x32x16_bf16 v[96:111], v[180:183], v[172:175], v[48:63]
	v_cvt_pk_bf16_f32 v162, v84, v85
	v_cvt_pk_bf16_f32 v163, v86, v87
	ds_read_b64_tr_b16 v[84:85], v188 offset:25600
	ds_read_b64_tr_b16 v[86:87], v188 offset:26112
	v_add_f32_e32 v144, v90, v144
	v_add_f32_e32 v144, v91, v144
	v_add_f32_e32 v144, v92, v144
	v_add_f32_e32 v144, v93, v144
	v_cvt_pk_bf16_f32 v156, v88, v89
	v_cvt_pk_bf16_f32 v157, v90, v91
	s_waitcnt lgkmcnt(11)
	v_mfma_f32_32x32x16_bf16 v[112:127], v[184:187], v[168:171], v[112:127]
	ds_read_b64_tr_b16 v[88:89], v188 offset:29696
	ds_read_b64_tr_b16 v[90:91], v188 offset:30208
	s_waitcnt lgkmcnt(12)
	v_mfma_f32_32x32x16_bf16 v[96:111], v[176:179], v[168:171], v[96:111]
	v_add_f32_e32 v144, v94, v144
	v_add_f32_e32 v144, v95, v144
	v_add_f32_e32 v144, v64, v144
	v_add_f32_e32 v144, v65, v144
	v_cvt_pk_bf16_f32 v158, v92, v93
	v_cvt_pk_bf16_f32 v159, v94, v95
	ds_read_b64_tr_b16 v[92:93], v188 offset:26624
	ds_read_b64_tr_b16 v[94:95], v188 offset:27136
	s_waitcnt lgkmcnt(13)
	v_mfma_f32_32x32x16_bf16 v[112:127], v[140:143], v[164:167], v[112:127]
	v_add_f32_e32 v140, v66, v144
	v_add_f32_e32 v140, v67, v140
	v_add_f32_e32 v140, v68, v140
	v_add_f32_e32 v140, v69, v140
	v_cvt_pk_bf16_f32 v148, v64, v65
	v_cvt_pk_bf16_f32 v149, v66, v67
	ds_read_b64_tr_b16 v[64:65], v188 offset:30720
	ds_read_b64_tr_b16 v[66:67], v188 offset:31232
	s_waitcnt lgkmcnt(14)
	v_mfma_f32_32x32x16_bf16 v[96:111], v[136:139], v[164:167], v[96:111]
	v_add_f32_e32 v136, v70, v140
	v_add_f32_e32 v136, v71, v136
	v_add_f32_e32 v136, v72, v136
	v_add_f32_e32 v136, v73, v136
	v_cvt_pk_bf16_f32 v150, v68, v69
	v_cvt_pk_bf16_f32 v151, v70, v71
	ds_read_b64_tr_b16 v[68:69], v188 offset:27648
	ds_read_b64_tr_b16 v[70:71], v188 offset:28160
	s_waitcnt lgkmcnt(14)
	v_mfma_f32_32x32x16_bf16 v[112:127], v[132:135], v[152:155], v[112:127]
	v_add_f32_e32 v132, v74, v136
	v_add_f32_e32 v132, v75, v132
	v_add_f32_e32 v132, v76, v132
	v_add_f32_e32 v132, v77, v132
	v_cvt_pk_bf16_f32 v144, v72, v73
	v_cvt_pk_bf16_f32 v145, v74, v75
	ds_read_b64_tr_b16 v[72:73], v188 offset:31744
	ds_read_b64_tr_b16 v[74:75], v188 offset:32256
	v_mfma_f32_32x32x16_bf16 v[96:111], v[128:131], v[152:155], v[96:111]
	v_add_f32_e32 v128, v78, v132
	v_add_f32_e32 v128, v79, v128
	v_add_f32_e32 v128, 0, v128
	v_cvt_pk_bf16_f32 v146, v76, v77
	v_cvt_pk_bf16_f32 v147, v78, v79
	s_cmp_eq_u32 s98, 0
	s_cbranch_scc1 .Lstg_a_mid_skip
	s_cmp_eq_i32 s21, -1
	s_cbranch_scc1 .Lstg_a_mid_skip
	s_waitcnt vmcnt(0) lgkmcnt(0)
	s_barrier
.Lstg_a_mid_skip:
	s_add_i32 m0, s23, s18
	v_lshl_add_u64 v[76:77], v[226:227], 0, s[86:87]
	global_load_lds_dwordx4 v[76:77], off
	s_add_i32 m0, s22, s19
	v_lshl_add_u64 v[76:77], v[224:225], 0, s[90:91]
	global_load_lds_dwordx4 v[76:77], off
	v_add_f32_e32 v188, v219, v128
	s_waitcnt lgkmcnt(14)
	v_mfma_f32_32x32x16_bf16 v[16:31], v[160:163], v[234:237], v[16:31]
	v_exp_f32_e32 v112, v112
	v_exp_f32_e32 v113, v113
	v_exp_f32_e32 v114, v114
	v_exp_f32_e32 v115, v115
	s_waitcnt lgkmcnt(12)
	v_mfma_f32_32x32x16_bf16 v[32:47], v[160:163], v[80:83], v[32:47]
	v_exp_f32_e32 v116, v116
	v_exp_f32_e32 v117, v117
	v_exp_f32_e32 v118, v118
	v_exp_f32_e32 v119, v119
	v_add_u32_e32 v80, s14, v242
	ds_read_b128 v[76:79], v80
	ds_read_b128 v[132:135], v80 offset:512
	s_waitcnt lgkmcnt(12)
	v_mfma_f32_32x32x16_bf16 v[16:31], v[156:159], v[84:87], v[16:31]
	v_exp_f32_e32 v120, v120
	v_exp_f32_e32 v121, v121
	v_exp_f32_e32 v122, v122
	v_exp_f32_e32 v123, v123
	ds_read_b128 v[136:139], v80 offset:2048
	ds_read_b128 v[140:143], v80 offset:2560
	s_waitcnt lgkmcnt(12)
	v_mfma_f32_32x32x16_bf16 v[32:47], v[156:159], v[88:91], v[32:47]
	v_exp_f32_e32 v124, v124
	v_exp_f32_e32 v125, v125
	v_exp_f32_e32 v126, v126
	v_exp_f32_e32 v127, v127
	ds_read_b128 v[176:179], v80 offset:4096
	ds_read_b128 v[180:183], v80 offset:4608
	s_waitcnt lgkmcnt(12)
	v_mfma_f32_32x32x16_bf16 v[16:31], v[148:151], v[92:95], v[16:31]
	v_exp_f32_e32 v96, v96
	v_exp_f32_e32 v97, v97
	v_exp_f32_e32 v98, v98
	v_exp_f32_e32 v99, v99
	ds_read_b128 v[184:187], v80 offset:6144
	ds_read_b128 v[128:131], v80 offset:6656
	s_waitcnt lgkmcnt(12)
	v_mfma_f32_32x32x16_bf16 v[32:47], v[148:151], v[64:67], v[32:47]
	v_exp_f32_e32 v100, v100
	v_exp_f32_e32 v101, v101
	v_exp_f32_e32 v102, v102
	v_exp_f32_e32 v103, v103
	s_waitcnt lgkmcnt(10)
	v_mfma_f32_32x32x16_bf16 v[16:31], v[144:147], v[68:71], v[16:31]
	v_exp_f32_e32 v104, v104
	v_exp_f32_e32 v105, v105
	v_exp_f32_e32 v106, v106
	v_exp_f32_e32 v107, v107
	s_waitcnt lgkmcnt(8)
	v_mfma_f32_32x32x16_bf16 v[32:47], v[144:147], v[72:75], v[32:47]
	v_exp_f32_e32 v108, v108
	v_exp_f32_e32 v109, v109
	v_exp_f32_e32 v110, v110
	v_exp_f32_e32 v111, v111
	s_cmp_eq_u32 s98, 0
	s_cbranch_scc0 .Lstg_a_end_b
	s_waitcnt vmcnt(1) lgkmcnt(0)
	s_barrier
	s_branch .Lstg_a_end_done

; #define WAIT_BAR(N) asm volatile("s_waitcnt vmcnt(" #N ") lgkmcnt(0)\n\ts_barrier" ::: "memory")
;   #define RESC() do { } while (0)
;   #define ROT() do { sl_prev = sl_cur; sl_cur = sl_next; sl_next = (sl_next == (NSLOT - 1) * SLOTB) ? 0 : sl_next + SLOTB; } while (0)
; template <int THRL> __device__ __forceinline__ void attn_unit(const int tid, const float mfix, int q0, int NT, const bf16* Qh, const bf16* __restrict__ Kh, const bf16* __restrict__ Vh, const bf16* Zh, bf16* Oh, const long PQ, const long PO, char* shm) {
;     ...
;   int t = 1;
;   for (; t + 5 < NT; t += 2) {
;     STEP(pB0, pB1, pA0, pA1, t, true, true, true);     WAIT_BAR(2); RESC(); ROT();
;     STEP(pA0, pA1, pB0, pB1, t + 1, true, true, true); WAIT_BAR(2); RESC(); ROT();
.Lstg_a_end_done:
	s_add_i32 s16, s23, 0x2000
	s_cmpk_lg_i32 s23, 0x4000
	s_cselect_b32 s22, s16, 0
	v_add_u32_e32 v219, s15, v244
	ds_read_b64_tr_b16 v[234:235], v219 offset:24576
	ds_read_b64_tr_b16 v[236:237], v219 offset:25088
	s_waitcnt lgkmcnt(9)
	v_mfma_f32_32x32x16_bf16 v[80:95], v[76:79], v[172:175], v[48:63]
	v_add_f32_e32 v64, v112, v113
	v_add_f32_e32 v64, v114, v64
	v_add_f32_e32 v64, v115, v64
	v_add_f32_e32 v64, v116, v64
	v_add_f32_e32 v64, v117, v64
	v_cvt_pk_bf16_f32 v160, v112, v113
	v_cvt_pk_bf16_f32 v161, v114, v115
	ds_read_b64_tr_b16 v[112:113], v219 offset:28672
	ds_read_b64_tr_b16 v[114:115], v219 offset:29184
	v_add_f32_e32 v64, v118, v64
	v_add_f32_e32 v64, v119, v64
	v_add_f32_e32 v64, v120, v64
	v_add_f32_e32 v144, v121, v64
	s_waitcnt lgkmcnt(10)
	v_mfma_f32_32x32x16_bf16 v[64:79], v[132:135], v[172:175], v[48:63]
	v_cvt_pk_bf16_f32 v162, v116, v117
	v_cvt_pk_bf16_f32 v163, v118, v119
	ds_read_b64_tr_b16 v[116:117], v219 offset:25600
	ds_read_b64_tr_b16 v[118:119], v219 offset:26112
	s_waitcnt lgkmcnt(11)
	v_mfma_f32_32x32x16_bf16 v[80:95], v[136:139], v[168:171], v[80:95]
	v_add_f32_e32 v132, v122, v144
	v_add_f32_e32 v132, v123, v132
	v_add_f32_e32 v132, v124, v132
	v_add_f32_e32 v132, v125, v132
	v_cvt_pk_bf16_f32 v156, v120, v121
	v_cvt_pk_bf16_f32 v157, v122, v123
	ds_read_b64_tr_b16 v[120:121], v219 offset:29696
	ds_read_b64_tr_b16 v[122:123], v219 offset:30208
	s_waitcnt lgkmcnt(12)
	v_mfma_f32_32x32x16_bf16 v[64:79], v[140:143], v[168:171], v[64:79]
	v_add_f32_e32 v132, v126, v132
	v_add_f32_e32 v132, v127, v132
	v_add_f32_e32 v132, v96, v132
	v_add_f32_e32 v132, v97, v132
	v_cvt_pk_bf16_f32 v158, v124, v125
	v_cvt_pk_bf16_f32 v159, v126, v127
	ds_read_b64_tr_b16 v[124:125], v219 offset:26624
	ds_read_b64_tr_b16 v[126:127], v219 offset:27136
	s_waitcnt lgkmcnt(13)
	v_mfma_f32_32x32x16_bf16 v[80:95], v[176:179], v[164:167], v[80:95]
	v_add_f32_e32 v132, v98, v132
	v_add_f32_e32 v132, v99, v132
	v_add_f32_e32 v132, v100, v132
	v_add_f32_e32 v132, v101, v132
	v_cvt_pk_bf16_f32 v148, v96, v97
	v_cvt_pk_bf16_f32 v149, v98, v99
	ds_read_b64_tr_b16 v[228:229], v219 offset:30720
	ds_read_b64_tr_b16 v[230:231], v219 offset:31232
	s_waitcnt lgkmcnt(14)
	v_mfma_f32_32x32x16_bf16 v[64:79], v[180:183], v[164:167], v[64:79]
	v_add_f32_e32 v96, v102, v132
	v_add_f32_e32 v96, v103, v96
	v_add_f32_e32 v96, v104, v96
	v_add_f32_e32 v96, v105, v96
	v_cvt_pk_bf16_f32 v150, v100, v101
	v_cvt_pk_bf16_f32 v151, v102, v103
	ds_read_b64_tr_b16 v[100:101], v219 offset:27648
	ds_read_b64_tr_b16 v[102:103], v219 offset:28160
	s_waitcnt lgkmcnt(14)
	v_mfma_f32_32x32x16_bf16 v[80:95], v[184:187], v[152:155], v[80:95]
	v_add_f32_e32 v96, v106, v96
	v_add_f32_e32 v96, v107, v96
	v_add_f32_e32 v96, v108, v96
	v_add_f32_e32 v96, v109, v96
	v_cvt_pk_bf16_f32 v144, v104, v105
	v_cvt_pk_bf16_f32 v145, v106, v107
	ds_read_b64_tr_b16 v[104:105], v219 offset:31744
	ds_read_b64_tr_b16 v[106:107], v219 offset:32256
	v_mfma_f32_32x32x16_bf16 v[64:79], v[128:131], v[152:155], v[64:79]
	v_add_f32_e32 v96, v110, v96
	v_add_f32_e32 v96, v111, v96
	v_add_f32_e32 v96, 0, v96
	v_cvt_pk_bf16_f32 v146, v108, v109
	v_cvt_pk_bf16_f32 v147, v110, v111
	v_add_f32_e32 v219, v188, v96
	s_cmp_eq_u32 s98, 0
	s_cbranch_scc1 .Lstg_b_mid_skip
	s_waitcnt vmcnt(0) lgkmcnt(0)
	s_barrier
.Lstg_b_mid_skip:
	s_add_i32 m0, s22, s18
	v_lshl_add_u64 v[226:227], v[226:227], 0, s[88:89]
	global_load_lds_dwordx4 v[226:227], off
	s_mov_b64 s[16:17], 0x348000
	s_add_i32 m0, s23, s19
	v_lshl_add_u64 v[96:97], v[224:225], 0, s[16:17]
	global_load_lds_dwordx4 v[96:97], off
	s_waitcnt lgkmcnt(14)
	v_mfma_f32_32x32x16_bf16 v[16:31], v[160:163], v[234:237], v[16:31]
	v_exp_f32_e32 v80, v80
	v_exp_f32_e32 v81, v81
	v_exp_f32_e32 v82, v82
	v_exp_f32_e32 v83, v83
	s_waitcnt lgkmcnt(12)
	v_mfma_f32_32x32x16_bf16 v[32:47], v[160:163], v[112:115], v[32:47]
	v_exp_f32_e32 v84, v84
	v_exp_f32_e32 v85, v85
	v_exp_f32_e32 v86, v86
	v_exp_f32_e32 v87, v87
	v_add_u32_e32 v108, s22, v242
	ds_read_b128 v[96:99], v108
	ds_read_b128 v[180:183], v108 offset:512
	s_waitcnt lgkmcnt(12)
	v_mfma_f32_32x32x16_bf16 v[16:31], v[156:159], v[116:119], v[16:31]
	v_exp_f32_e32 v88, v88
	v_exp_f32_e32 v89, v89
	v_exp_f32_e32 v90, v90
	v_exp_f32_e32 v91, v91
	ds_read_b128 v[184:187], v108 offset:2048
	ds_read_b128 v[176:179], v108 offset:2560
	s_waitcnt lgkmcnt(12)
	v_mfma_f32_32x32x16_bf16 v[32:47], v[156:159], v[120:123], v[32:47]
	v_exp_f32_e32 v92, v92
	v_exp_f32_e32 v93, v93
	v_exp_f32_e32 v94, v94
	v_exp_f32_e32 v95, v95
	ds_read_b128 v[140:143], v108 offset:4096
	ds_read_b128 v[136:139], v108 offset:4608
	s_waitcnt lgkmcnt(12)
	v_mfma_f32_32x32x16_bf16 v[16:31], v[148:151], v[124:127], v[16:31]
	v_exp_f32_e32 v64, v64
	v_exp_f32_e32 v65, v65
	v_exp_f32_e32 v66, v66
	v_exp_f32_e32 v67, v67
	ds_read_b128 v[132:135], v108 offset:6144
	ds_read_b128 v[128:131], v108 offset:6656
	s_waitcnt lgkmcnt(12)
	v_mfma_f32_32x32x16_bf16 v[32:47], v[148:151], v[228:231], v[32:47]
	v_exp_f32_e32 v68, v68
	v_exp_f32_e32 v69, v69
	v_exp_f32_e32 v70, v70
	v_exp_f32_e32 v71, v71
	s_waitcnt lgkmcnt(10)
	v_mfma_f32_32x32x16_bf16 v[16:31], v[144:147], v[100:103], v[16:31]
	v_exp_f32_e32 v72, v72
	v_exp_f32_e32 v73, v73
	v_exp_f32_e32 v74, v74
	v_exp_f32_e32 v75, v75
	s_waitcnt lgkmcnt(8)
	v_mfma_f32_32x32x16_bf16 v[32:47], v[144:147], v[104:107], v[32:47]
	v_exp_f32_e32 v76, v76
	v_exp_f32_e32 v77, v77
	v_exp_f32_e32 v78, v78
	v_exp_f32_e32 v79, v79
	s_add_i32 s15, s22, 0x2000
	s_cmp_eq_u32 s98, 0
	s_cbranch_scc0 .Lstg_b_end_b
	s_waitcnt vmcnt(1) lgkmcnt(0)
	s_barrier
	s_branch .Lstg_b_end_done
.Lstg_b_end_b:
	s_cmpk_eq_i32 s21, 0xf7
	s_cbranch_scc0 .Lstg_b_end_nobar
	s_waitcnt vmcnt(2) lgkmcnt(0)
	s_barrier
	s_branch .Lstg_b_end_done

; #define WAIT_BAR(N) asm volatile("s_waitcnt vmcnt(" #N ") lgkmcnt(0)\n\ts_barrier" ::: "memory")
;   #define RESC() do { } while (0)
;   #define ROT() do { sl_prev = sl_cur; sl_cur = sl_next; sl_next = (sl_next == (NSLOT - 1) * SLOTB) ? 0 : sl_next + SLOTB; } while (0)
;   #define ENDW(tt) do { if ((tt) + 3 < NT) { WAIT_BAR(2); } else if ((tt) + 2 < NT) { WAIT_BAR(1); } else { WAIT_BAR(0); } } while (0)
; template <int THRL> __device__ __forceinline__ void attn_unit(const int tid, const float mfix, int q0, int NT, const bf16* Qh, const bf16* __restrict__ Kh, const bf16* __restrict__ Vh, const bf16* Zh, bf16* Oh, const long PQ, const long PO, char* shm) {
;     ...
;   int t = 1;
;   for (; t + 5 < NT; t += 2) {
;     STEP(pB0, pB1, pA0, pA1, t, true, true, true);     WAIT_BAR(2); RESC(); ROT();
;     STEP(pA0, pA1, pB0, pB1, t + 1, true, true, true); WAIT_BAR(2); RESC(); ROT();
;   }
;     ...
;   for (; t + 1 < NT; t += 2) {
;     STEP(pB0, pB1, pA0, pA1, t, (t + 3 < NT), (t + 1 < NT), (t + 1 < NT));         ENDW(t);     RESC(); ROT();
;     STEP(pA0, pA1, pB0, pB1, t + 1, (t + 4 < NT), (t + 2 < NT), (t + 2 < NT));     ENDW(t + 1); RESC(); ROT();
.Lstg_b_end_done:
	s_cmpk_lg_i32 s22, 0x4000
	s_cselect_b32 s23, s15, 0
	s_add_i32 s21, s21, 2
	v_lshl_add_u64 v[224:225], v[224:225], 0, s[88:89]
	s_cmpk_gt_u32 s21, 0xf8
	s_mov_b32 s24, s14
	s_cbranch_scc0 .LBB0_388
	s_and_b32 s15, s20, 0x3fffffc0
	s_lshl_b32 s15, s15, 2
	s_add_i32 s16, s15, 0
	v_add_u32_e32 v188, s14, v244
	ds_read_b64_tr_b16 v[224:225], v188 offset:24576
	ds_read_b64_tr_b16 v[226:227], v188 offset:25088
	v_add_f32_e32 v100, v80, v81
	v_add_f32_e32 v100, v82, v100
	v_add_f32_e32 v100, v83, v100
	v_add_f32_e32 v100, v84, v100
	v_add_f32_e32 v100, v85, v100
	v_cvt_pk_bf16_f32 v160, v80, v81
	v_cvt_pk_bf16_f32 v161, v82, v83
	s_waitcnt lgkmcnt(9)
	v_mfma_f32_32x32x16_bf16 v[112:127], v[96:99], v[172:175], v[48:63]
	ds_read_b64_tr_b16 v[80:81], v188 offset:28672
	ds_read_b64_tr_b16 v[82:83], v188 offset:29184
	v_add_f32_e32 v96, v86, v100
	v_add_f32_e32 v96, v87, v96
	v_add_f32_e32 v96, v88, v96
	v_add_f32_e32 v144, v89, v96
	v_cvt_pk_bf16_f32 v162, v84, v85
	v_cvt_pk_bf16_f32 v163, v86, v87
	s_waitcnt lgkmcnt(10)
	v_mfma_f32_32x32x16_bf16 v[96:111], v[180:183], v[172:175], v[48:63]
	ds_read_b64_tr_b16 v[84:85], v188 offset:25600
	ds_read_b64_tr_b16 v[86:87], v188 offset:26112
	v_add_f32_e32 v144, v90, v144
	v_add_f32_e32 v144, v91, v144
	v_add_f32_e32 v144, v92, v144
	v_add_f32_e32 v144, v93, v144
	v_cvt_pk_bf16_f32 v156, v88, v89
	v_cvt_pk_bf16_f32 v157, v90, v91
	s_waitcnt lgkmcnt(11)
	v_mfma_f32_32x32x16_bf16 v[112:127], v[184:187], v[168:171], v[112:127]
	ds_read_b64_tr_b16 v[88:89], v188 offset:29696
	ds_read_b64_tr_b16 v[90:91], v188 offset:30208
	v_add_f32_e32 v144, v94, v144
	v_add_f32_e32 v144, v95, v144
	v_add_f32_e32 v144, v64, v144
	v_add_f32_e32 v144, v65, v144
	v_cvt_pk_bf16_f32 v158, v92, v93
	v_cvt_pk_bf16_f32 v159, v94, v95
	s_waitcnt lgkmcnt(12)
	v_mfma_f32_32x32x16_bf16 v[96:111], v[176:179], v[168:171], v[96:111]
	ds_read_b64_tr_b16 v[92:93], v188 offset:26624
	ds_read_b64_tr_b16 v[94:95], v188 offset:27136
	s_waitcnt lgkmcnt(13)
	v_mfma_f32_32x32x16_bf16 v[112:127], v[140:143], v[164:167], v[112:127]
	v_add_f32_e32 v140, v66, v144
	v_add_f32_e32 v140, v67, v140
	v_add_f32_e32 v140, v68, v140
	v_add_f32_e32 v140, v69, v140
	v_cvt_pk_bf16_f32 v148, v64, v65
	v_cvt_pk_bf16_f32 v149, v66, v67
	ds_read_b64_tr_b16 v[64:65], v188 offset:30720
	ds_read_b64_tr_b16 v[66:67], v188 offset:31232
	s_waitcnt lgkmcnt(14)
	v_mfma_f32_32x32x16_bf16 v[96:111], v[136:139], v[164:167], v[96:111]
	v_add_f32_e32 v136, v70, v140
	v_add_f32_e32 v136, v71, v136
	v_add_f32_e32 v136, v72, v136
	v_add_f32_e32 v136, v73, v136
	v_cvt_pk_bf16_f32 v150, v68, v69
	v_cvt_pk_bf16_f32 v151, v70, v71
	ds_read_b64_tr_b16 v[68:69], v188 offset:27648
	ds_read_b64_tr_b16 v[70:71], v188 offset:28160
	s_waitcnt lgkmcnt(14)
	v_mfma_f32_32x32x16_bf16 v[112:127], v[132:135], v[152:155], v[112:127]
	v_add_f32_e32 v132, v74, v136
	v_add_f32_e32 v132, v75, v132
	v_add_f32_e32 v132, v76, v132
	v_add_f32_e32 v132, v77, v132
	v_cvt_pk_bf16_f32 v144, v72, v73
	v_cvt_pk_bf16_f32 v145, v74, v75
	ds_read_b64_tr_b16 v[72:73], v188 offset:31744
	ds_read_b64_tr_b16 v[74:75], v188 offset:32256
	v_mfma_f32_32x32x16_bf16 v[96:111], v[128:131], v[152:155], v[96:111]
	v_add_f32_e32 v128, v78, v132
	v_add_f32_e32 v128, v79, v128
	v_add_f32_e32 v128, 0, v128
	v_cvt_pk_bf16_f32 v146, v76, v77
	v_cvt_pk_bf16_f32 v147, v78, v79
	s_add_i32 s14, s22, s19
	v_lshl_add_u64 v[76:77], v[222:223], 0, s[92:93]
	s_mov_b32 s15, m0
	s_mov_b32 m0, s14
	s_nop 0
	global_load_lds_dwordx4 v[76:77], off
	s_mov_b32 m0, s15
	s_mov_b64 s[14:15], 0xceb8000
	v_lshl_add_u64 v[76:77], v[220:221], 0, s[14:15]
	s_add_i32 s14, s23, s18
	s_mov_b32 s15, m0
	s_mov_b32 m0, s14
	s_nop 0
	global_load_lds_dwordx4 v[76:77], off
	s_mov_b32 m0, s15
	v_add_f32_e32 v188, v219, v128
	s_waitcnt lgkmcnt(14)
	v_mfma_f32_32x32x16_bf16 v[16:31], v[160:163], v[224:227], v[16:31]
	v_exp_f32_e32 v112, v112
	v_exp_f32_e32 v113, v113
	v_exp_f32_e32 v114, v114
	v_exp_f32_e32 v115, v115
	s_waitcnt lgkmcnt(12)
	v_mfma_f32_32x32x16_bf16 v[32:47], v[160:163], v[80:83], v[32:47]
	v_exp_f32_e32 v116, v116
	v_exp_f32_e32 v117, v117
	v_exp_f32_e32 v118, v118
	v_exp_f32_e32 v119, v119
	v_add_u32_e32 v80, s23, v242
	ds_read_b128 v[76:79], v80
	ds_read_b128 v[176:179], v80 offset:512
	s_waitcnt lgkmcnt(12)
	v_mfma_f32_32x32x16_bf16 v[16:31], v[156:159], v[84:87], v[16:31]
	v_exp_f32_e32 v120, v120
	v_exp_f32_e32 v121, v121
	v_exp_f32_e32 v122, v122
	v_exp_f32_e32 v123, v123
	ds_read_b128 v[84:87], v80 offset:2048
	ds_read_b128 v[180:183], v80 offset:2560
	s_waitcnt lgkmcnt(12)
	v_mfma_f32_32x32x16_bf16 v[32:47], v[156:159], v[88:91], v[32:47]
	v_exp_f32_e32 v124, v124
	v_exp_f32_e32 v125, v125
	v_exp_f32_e32 v126, v126
	v_exp_f32_e32 v127, v127
	ds_read_b128 v[88:91], v80 offset:4096
	ds_read_b128 v[184:187], v80 offset:4608
	s_waitcnt lgkmcnt(12)
	v_mfma_f32_32x32x16_bf16 v[16:31], v[148:151], v[92:95], v[16:31]
	v_exp_f32_e32 v96, v96
	v_exp_f32_e32 v97, v97
	v_exp_f32_e32 v98, v98
	v_exp_f32_e32 v99, v99
	ds_read_b128 v[92:95], v80 offset:6144
	ds_read_b128 v[80:83], v80 offset:6656
	s_waitcnt lgkmcnt(12)
	v_mfma_f32_32x32x16_bf16 v[32:47], v[148:151], v[64:67], v[32:47]
	v_exp_f32_e32 v100, v100
	v_exp_f32_e32 v101, v101
	v_exp_f32_e32 v102, v102
	v_exp_f32_e32 v103, v103
	s_waitcnt lgkmcnt(10)
	v_mfma_f32_32x32x16_bf16 v[16:31], v[144:147], v[68:71], v[16:31]
	v_exp_f32_e32 v104, v104
	v_exp_f32_e32 v105, v105
	v_exp_f32_e32 v106, v106
	v_exp_f32_e32 v107, v107
	s_waitcnt lgkmcnt(8)
	v_mfma_f32_32x32x16_bf16 v[32:47], v[144:147], v[72:75], v[32:47]
	v_exp_f32_e32 v108, v108
	v_exp_f32_e32 v109, v109
	v_exp_f32_e32 v110, v110
	v_exp_f32_e32 v111, v111
	s_waitcnt vmcnt(2) lgkmcnt(0)
	s_barrier
; #define WAIT_BAR(N) asm volatile("s_waitcnt vmcnt(" #N ") lgkmcnt(0)\n\ts_barrier" ::: "memory")
;   #define RESC() do { } while (0)
;   #define ROT() do { sl_prev = sl_cur; sl_cur = sl_next; sl_next = (sl_next == (NSLOT - 1) * SLOTB) ? 0 : sl_next + SLOTB; } while (0)
;   #define ENDW(tt) do { if ((tt) + 3 < NT) { WAIT_BAR(2); } else if ((tt) + 2 < NT) { WAIT_BAR(1); } else { WAIT_BAR(0); } } while (0)
; template <int THRL> __device__ __forceinline__ void attn_unit(const int tid, const float mfix, int q0, int NT, const bf16* Qh, const bf16* __restrict__ Kh, const bf16* __restrict__ Vh, const bf16* Zh, bf16* Oh, const long PQ, const long PO, char* shm) {
;     ...
;   int t = 1;
;   for (; t + 5 < NT; t += 2) {
;     STEP(pB0, pB1, pA0, pA1, t, true, true, true);     WAIT_BAR(2); RESC(); ROT();
;     STEP(pA0, pA1, pB0, pB1, t + 1, true, true, true); WAIT_BAR(2); RESC(); ROT();
;   }
;     ...
;   for (; t + 1 < NT; t += 2) {
;     STEP(pB0, pB1, pA0, pA1, t, (t + 3 < NT), (t + 1 < NT), (t + 1 < NT));         ENDW(t);     RESC(); ROT();
;     STEP(pA0, pA1, pB0, pB1, t + 1, (t + 4 < NT), (t + 2 < NT), (t + 2 < NT));     ENDW(t + 1); RESC(); ROT();
	s_add_i32 s14, s23, 0x2000
	s_cmpk_lg_i32 s23, 0x4000
	s_cselect_b32 s15, s14, 0
	v_add_u32_e32 v219, s22, v244
	ds_read_b64_tr_b16 v[224:225], v219 offset:24576
	ds_read_b64_tr_b16 v[226:227], v219 offset:25088
	v_add_f32_e32 v64, v112, v113
	v_add_f32_e32 v64, v114, v64
	v_add_f32_e32 v64, v115, v64
	v_add_f32_e32 v64, v116, v64
	v_add_f32_e32 v64, v117, v64
	v_cvt_pk_bf16_f32 v160, v112, v113
	v_cvt_pk_bf16_f32 v161, v114, v115
	s_waitcnt lgkmcnt(9)
	v_mfma_f32_32x32x16_bf16 v[128:143], v[76:79], v[172:175], v[48:63]
	ds_read_b64_tr_b16 v[112:113], v219 offset:28672
	ds_read_b64_tr_b16 v[114:115], v219 offset:29184
	v_add_f32_e32 v64, v118, v64
	v_add_f32_e32 v64, v119, v64
	v_add_f32_e32 v64, v120, v64
	v_add_f32_e32 v144, v121, v64
	s_waitcnt lgkmcnt(10)
	v_mfma_f32_32x32x16_bf16 v[64:79], v[176:179], v[172:175], v[48:63]
	v_cvt_pk_bf16_f32 v162, v116, v117
	v_cvt_pk_bf16_f32 v163, v118, v119
	ds_read_b64_tr_b16 v[116:117], v219 offset:25600
	ds_read_b64_tr_b16 v[118:119], v219 offset:26112
	s_waitcnt lgkmcnt(11)
	v_mfma_f32_32x32x16_bf16 v[128:143], v[84:87], v[168:171], v[128:143]
	v_add_f32_e32 v84, v122, v144
	v_add_f32_e32 v84, v123, v84
	v_add_f32_e32 v84, v124, v84
	v_add_f32_e32 v144, v125, v84
	v_cvt_pk_bf16_f32 v156, v120, v121
	v_cvt_pk_bf16_f32 v157, v122, v123
	ds_read_b64_tr_b16 v[84:85], v219 offset:29696
	ds_read_b64_tr_b16 v[86:87], v219 offset:30208
	s_waitcnt lgkmcnt(12)
	v_mfma_f32_32x32x16_bf16 v[64:79], v[180:183], v[168:171], v[64:79]
	v_add_f32_e32 v120, v126, v144
	v_add_f32_e32 v120, v127, v120
	v_add_f32_e32 v120, v96, v120
	v_add_f32_e32 v144, v97, v120
	v_cvt_pk_bf16_f32 v158, v124, v125
	v_cvt_pk_bf16_f32 v159, v126, v127
	ds_read_b64_tr_b16 v[120:121], v219 offset:26624
	ds_read_b64_tr_b16 v[122:123], v219 offset:27136
	s_waitcnt lgkmcnt(13)
	v_mfma_f32_32x32x16_bf16 v[128:143], v[88:91], v[164:167], v[128:143]
	v_add_f32_e32 v88, v98, v144
	v_add_f32_e32 v88, v99, v88
	v_add_f32_e32 v88, v100, v88
	v_add_f32_e32 v124, v101, v88
	v_cvt_pk_bf16_f32 v148, v96, v97
	v_cvt_pk_bf16_f32 v149, v98, v99
	ds_read_b64_tr_b16 v[88:89], v219 offset:30720
	ds_read_b64_tr_b16 v[90:91], v219 offset:31232
	s_waitcnt lgkmcnt(14)
	v_mfma_f32_32x32x16_bf16 v[64:79], v[184:187], v[164:167], v[64:79]
	v_add_f32_e32 v96, v102, v124
	v_add_f32_e32 v96, v103, v96
	v_add_f32_e32 v96, v104, v96
	v_add_f32_e32 v96, v105, v96
	v_cvt_pk_bf16_f32 v150, v100, v101
	v_cvt_pk_bf16_f32 v151, v102, v103
	ds_read_b64_tr_b16 v[100:101], v219 offset:27648
	ds_read_b64_tr_b16 v[102:103], v219 offset:28160
	s_waitcnt lgkmcnt(14)
	v_mfma_f32_32x32x16_bf16 v[128:143], v[92:95], v[152:155], v[128:143]
	v_add_f32_e32 v92, v106, v96
	v_add_f32_e32 v92, v107, v92
	v_add_f32_e32 v92, v108, v92
	v_add_f32_e32 v96, v109, v92
	v_cvt_pk_bf16_f32 v144, v104, v105
	v_cvt_pk_bf16_f32 v145, v106, v107
	ds_read_b64_tr_b16 v[92:93], v219 offset:31744
	ds_read_b64_tr_b16 v[94:95], v219 offset:32256
	v_mfma_f32_32x32x16_bf16 v[64:79], v[80:83], v[152:155], v[64:79]
	v_add_f32_e32 v80, v110, v96
	v_add_f32_e32 v80, v111, v80
	v_add_f32_e32 v80, 0, v80
	v_cvt_pk_bf16_f32 v146, v108, v109
	v_cvt_pk_bf16_f32 v147, v110, v111
	s_nop 0
	v_add_f32_e32 v188, v188, v80
	s_add_i32 s14, s23, s19
	v_lshl_add_u64 v[80:81], v[222:223], 0, s[94:95]
	s_mov_b32 s17, m0
	s_mov_b32 m0, s14
	s_nop 0
	global_load_lds_dwordx4 v[80:81], off
	s_mov_b32 m0, s17
	s_mov_b64 s[20:21], 0xcf8a000
	s_add_i32 s14, s15, s18
	v_lshl_add_u64 v[80:81], v[220:221], 0, s[20:21]
	s_mov_b32 s17, m0
	s_mov_b32 m0, s14
	s_nop 0
	global_load_lds_dwordx4 v[80:81], off
	s_mov_b32 m0, s17
	s_waitcnt lgkmcnt(14)
	v_mfma_f32_32x32x16_bf16 v[16:31], v[160:163], v[224:227], v[16:31]
	v_exp_f32_e32 v128, v128
	v_exp_f32_e32 v129, v129
	v_exp_f32_e32 v130, v130
	v_exp_f32_e32 v131, v131
	s_waitcnt lgkmcnt(12)
	v_mfma_f32_32x32x16_bf16 v[32:47], v[160:163], v[112:115], v[32:47]
	v_exp_f32_e32 v132, v132
	v_exp_f32_e32 v133, v133
	v_exp_f32_e32 v134, v134
	v_exp_f32_e32 v135, v135
	v_add_u32_e32 v96, s15, v242
	ds_read_b128 v[80:83], v96
	ds_read_b128 v[104:107], v96 offset:512
	s_waitcnt lgkmcnt(12)
	v_mfma_f32_32x32x16_bf16 v[16:31], v[156:159], v[116:119], v[16:31]
	v_exp_f32_e32 v136, v136
	v_exp_f32_e32 v137, v137
	v_exp_f32_e32 v138, v138
	v_exp_f32_e32 v139, v139
	ds_read_b128 v[108:111], v96 offset:2048
	ds_read_b128 v[176:179], v96 offset:2560
	s_waitcnt lgkmcnt(12)
	v_mfma_f32_32x32x16_bf16 v[32:47], v[156:159], v[84:87], v[32:47]
	v_exp_f32_e32 v140, v140
	v_exp_f32_e32 v141, v141
	v_exp_f32_e32 v142, v142
	v_exp_f32_e32 v143, v143
	ds_read_b128 v[180:183], v96 offset:4096
	ds_read_b128 v[184:187], v96 offset:4608
	s_waitcnt lgkmcnt(12)
	v_mfma_f32_32x32x16_bf16 v[16:31], v[148:151], v[120:123], v[16:31]
	v_exp_f32_e32 v64, v64
	v_exp_f32_e32 v65, v65
	v_exp_f32_e32 v66, v66
	v_exp_f32_e32 v67, v67
	ds_read_b128 v[222:225], v96 offset:6144
	ds_read_b128 v[96:99], v96 offset:6656
	s_waitcnt lgkmcnt(12)
	v_mfma_f32_32x32x16_bf16 v[32:47], v[148:151], v[88:91], v[32:47]
	v_exp_f32_e32 v68, v68
	v_exp_f32_e32 v69, v69
	v_exp_f32_e32 v70, v70
	v_exp_f32_e32 v71, v71
	s_waitcnt lgkmcnt(10)
	v_mfma_f32_32x32x16_bf16 v[16:31], v[144:147], v[100:103], v[16:31]
	v_exp_f32_e32 v72, v72
	v_exp_f32_e32 v73, v73
	v_exp_f32_e32 v74, v74
	v_exp_f32_e32 v75, v75
	s_waitcnt lgkmcnt(8)
	v_mfma_f32_32x32x16_bf16 v[32:47], v[144:147], v[92:95], v[32:47]
	v_exp_f32_e32 v76, v76
	v_exp_f32_e32 v77, v77
	v_exp_f32_e32 v78, v78
	v_exp_f32_e32 v79, v79
	s_waitcnt vmcnt(2) lgkmcnt(0)
	s_barrier
; #define WAIT_BAR(N) asm volatile("s_waitcnt vmcnt(" #N ") lgkmcnt(0)\n\ts_barrier" ::: "memory")
;   #define RESC() do { } while (0)
;   #define ROT() do { sl_prev = sl_cur; sl_cur = sl_next; sl_next = (sl_next == (NSLOT - 1) * SLOTB) ? 0 : sl_next + SLOTB; } while (0)
;   #define ENDW(tt) do { if ((tt) + 3 < NT) { WAIT_BAR(2); } else if ((tt) + 2 < NT) { WAIT_BAR(1); } else { WAIT_BAR(0); } } while (0)
; template <int THRL> __device__ __forceinline__ void attn_unit(const int tid, const float mfix, int q0, int NT, const bf16* Qh, const bf16* __restrict__ Kh, const bf16* __restrict__ Vh, const bf16* Zh, bf16* Oh, const long PQ, const long PO, char* shm) {
;     ...
;   int t = 1;
;   for (; t + 5 < NT; t += 2) {
;     STEP(pB0, pB1, pA0, pA1, t, true, true, true);     WAIT_BAR(2); RESC(); ROT();
;     STEP(pA0, pA1, pB0, pB1, t + 1, true, true, true); WAIT_BAR(2); RESC(); ROT();
;   }
;     ...
;   for (; t + 1 < NT; t += 2) {
;     STEP(pB0, pB1, pA0, pA1, t, (t + 3 < NT), (t + 1 < NT), (t + 1 < NT));         ENDW(t);     RESC(); ROT();
	s_add_i32 s14, s15, 0x2000
	s_cmpk_lg_i32 s15, 0x4000
	s_cselect_b32 s17, s14, 0
	v_add_u32_e32 v219, s23, v244
	ds_read_b64_tr_b16 v[100:101], v219 offset:24576
	ds_read_b64_tr_b16 v[102:103], v219 offset:25088
	v_add_f32_e32 v84, v128, v129
	v_add_f32_e32 v84, v130, v84
	v_add_f32_e32 v84, v131, v84
	v_add_f32_e32 v84, v132, v84
	v_add_f32_e32 v84, v133, v84
	v_cvt_pk_bf16_f32 v160, v128, v129
	v_cvt_pk_bf16_f32 v161, v130, v131
	s_waitcnt lgkmcnt(9)
	v_mfma_f32_32x32x16_bf16 v[112:127], v[80:83], v[172:175], v[48:63]
	ds_read_b64_tr_b16 v[128:129], v219 offset:28672
	ds_read_b64_tr_b16 v[130:131], v219 offset:29184
	v_add_f32_e32 v80, v134, v84
	v_add_f32_e32 v80, v135, v80
	v_add_f32_e32 v80, v136, v80
	v_add_f32_e32 v144, v137, v80
	v_cvt_pk_bf16_f32 v162, v132, v133
	v_cvt_pk_bf16_f32 v163, v134, v135
	s_waitcnt lgkmcnt(10)
	v_mfma_f32_32x32x16_bf16 v[80:95], v[104:107], v[172:175], v[48:63]
	ds_read_b64_tr_b16 v[104:105], v219 offset:25600
	ds_read_b64_tr_b16 v[106:107], v219 offset:26112
	s_waitcnt lgkmcnt(11)
	v_mfma_f32_32x32x16_bf16 v[112:127], v[108:111], v[168:171], v[112:127]
	v_add_f32_e32 v108, v138, v144
	v_add_f32_e32 v108, v139, v108
	v_add_f32_e32 v108, v140, v108
	v_add_f32_e32 v132, v141, v108
	v_cvt_pk_bf16_f32 v156, v136, v137
	v_cvt_pk_bf16_f32 v157, v138, v139
	ds_read_b64_tr_b16 v[108:109], v219 offset:29696
	ds_read_b64_tr_b16 v[110:111], v219 offset:30208
	v_add_f32_e32 v132, v142, v132
	v_add_f32_e32 v132, v143, v132
	v_add_f32_e32 v132, v64, v132
	v_add_f32_e32 v136, v65, v132
	v_cvt_pk_bf16_f32 v158, v140, v141
	v_cvt_pk_bf16_f32 v159, v142, v143
	s_waitcnt lgkmcnt(12)
	v_mfma_f32_32x32x16_bf16 v[80:95], v[176:179], v[168:171], v[80:95]
	ds_read_b64_tr_b16 v[132:133], v219 offset:26624
	ds_read_b64_tr_b16 v[134:135], v219 offset:27136
	v_add_f32_e32 v136, v66, v136
	v_add_f32_e32 v136, v67, v136
	v_add_f32_e32 v136, v68, v136
	v_add_f32_e32 v136, v69, v136
	v_cvt_pk_bf16_f32 v148, v64, v65
	v_cvt_pk_bf16_f32 v149, v66, v67
	s_waitcnt lgkmcnt(13)
	v_mfma_f32_32x32x16_bf16 v[112:127], v[180:183], v[164:167], v[112:127]
	ds_read_b64_tr_b16 v[64:65], v219 offset:30720
	ds_read_b64_tr_b16 v[66:67], v219 offset:31232
	v_add_f32_e32 v136, v70, v136
	v_add_f32_e32 v136, v71, v136
	v_add_f32_e32 v136, v72, v136
	v_add_f32_e32 v136, v73, v136
	v_cvt_pk_bf16_f32 v150, v68, v69
	v_cvt_pk_bf16_f32 v151, v70, v71
	s_waitcnt lgkmcnt(14)
	v_mfma_f32_32x32x16_bf16 v[80:95], v[184:187], v[164:167], v[80:95]
	ds_read_b64_tr_b16 v[68:69], v219 offset:27648
	ds_read_b64_tr_b16 v[70:71], v219 offset:28160
	v_add_f32_e32 v136, v74, v136
	v_add_f32_e32 v136, v75, v136
	v_add_f32_e32 v136, v76, v136
	v_add_f32_e32 v136, v77, v136
	v_cvt_pk_bf16_f32 v144, v72, v73
	v_cvt_pk_bf16_f32 v145, v74, v75
	s_waitcnt lgkmcnt(14)
	v_mfma_f32_32x32x16_bf16 v[112:127], v[222:225], v[152:155], v[112:127]
	ds_read_b64_tr_b16 v[72:73], v219 offset:31744
	ds_read_b64_tr_b16 v[74:75], v219 offset:32256
	v_mfma_f32_32x32x16_bf16 v[80:95], v[96:99], v[152:155], v[80:95]
	v_add_f32_e32 v96, v78, v136
	v_add_f32_e32 v96, v79, v96
	v_add_f32_e32 v96, 0, v96
	v_cvt_pk_bf16_f32 v146, v76, v77
	v_cvt_pk_bf16_f32 v147, v78, v79
	v_lshl_add_u64 v[76:77], v[220:221], 0, s[92:93]
	s_add_i32 s14, s17, s18
	s_mov_b32 s19, m0
	s_mov_b32 m0, s14
	s_nop 0
	global_load_lds_dwordx4 v[76:77], off
	s_mov_b32 m0, s19
	v_add_f32_e32 v188, v188, v96
	s_waitcnt lgkmcnt(14)
	v_mfma_f32_32x32x16_bf16 v[16:31], v[160:163], v[100:103], v[16:31]
	v_exp_f32_e32 v112, v112
	v_exp_f32_e32 v113, v113
	v_exp_f32_e32 v114, v114
	v_exp_f32_e32 v115, v115
	s_waitcnt lgkmcnt(12)
	v_mfma_f32_32x32x16_bf16 v[32:47], v[160:163], v[128:131], v[32:47]
	v_exp_f32_e32 v116, v116
	v_exp_f32_e32 v117, v117
	v_exp_f32_e32 v118, v118
	v_exp_f32_e32 v119, v119
	v_add_u32_e32 v96, s17, v242
	ds_read_b128 v[76:79], v96
	ds_read_b128 v[136:139], v96 offset:512
	s_waitcnt lgkmcnt(12)
	v_mfma_f32_32x32x16_bf16 v[16:31], v[156:159], v[104:107], v[16:31]
	v_exp_f32_e32 v120, v120
	v_exp_f32_e32 v121, v121
	v_exp_f32_e32 v122, v122
	v_exp_f32_e32 v123, v123
	ds_read_b128 v[140:143], v96 offset:2048
	ds_read_b128 v[176:179], v96 offset:2560
	s_waitcnt lgkmcnt(12)
	v_mfma_f32_32x32x16_bf16 v[32:47], v[156:159], v[108:111], v[32:47]
	v_exp_f32_e32 v124, v124
	v_exp_f32_e32 v125, v125
	v_exp_f32_e32 v126, v126
	v_exp_f32_e32 v127, v127
	ds_read_b128 v[180:183], v96 offset:4096
	ds_read_b128 v[184:187], v96 offset:4608
	s_waitcnt lgkmcnt(12)
	v_mfma_f32_32x32x16_bf16 v[16:31], v[148:151], v[132:135], v[16:31]
	v_exp_f32_e32 v80, v80
	v_exp_f32_e32 v81, v81
	v_exp_f32_e32 v82, v82
	v_exp_f32_e32 v83, v83
	ds_read_b128 v[132:135], v96 offset:6144
	ds_read_b128 v[128:131], v96 offset:6656
	s_waitcnt lgkmcnt(12)
	v_mfma_f32_32x32x16_bf16 v[32:47], v[148:151], v[64:67], v[32:47]
	v_exp_f32_e32 v84, v84
	v_exp_f32_e32 v85, v85
	v_exp_f32_e32 v86, v86
	v_exp_f32_e32 v87, v87
	s_waitcnt lgkmcnt(10)
	v_mfma_f32_32x32x16_bf16 v[16:31], v[144:147], v[68:71], v[16:31]
	v_exp_f32_e32 v88, v88
	v_exp_f32_e32 v89, v89
	v_exp_f32_e32 v90, v90
	v_exp_f32_e32 v91, v91
	s_waitcnt lgkmcnt(8)
	v_mfma_f32_32x32x16_bf16 v[32:47], v[144:147], v[72:75], v[32:47]
	v_exp_f32_e32 v92, v92
	v_exp_f32_e32 v93, v93
	v_exp_f32_e32 v94, v94
	v_exp_f32_e32 v95, v95
	s_waitcnt vmcnt(1) lgkmcnt(0)
	s_barrier
; #define WAIT_BAR(N) asm volatile("s_waitcnt vmcnt(" #N ") lgkmcnt(0)\n\ts_barrier" ::: "memory")
;   #define RESC() do { } while (0)
;   #define ROT() do { sl_prev = sl_cur; sl_cur = sl_next; sl_next = (sl_next == (NSLOT - 1) * SLOTB) ? 0 : sl_next + SLOTB; } while (0)
;   #define ENDW(tt) do { if ((tt) + 3 < NT) { WAIT_BAR(2); } else if ((tt) + 2 < NT) { WAIT_BAR(1); } else { WAIT_BAR(0); } } while (0)
; template <int THRL> __device__ __forceinline__ void attn_unit(const int tid, const float mfix, int q0, int NT, const bf16* Qh, const bf16* __restrict__ Kh, const bf16* __restrict__ Vh, const bf16* Zh, bf16* Oh, const long PQ, const long PO, char* shm) {
;     ...
;   int t = 1;
;   for (; t + 5 < NT; t += 2) {
;     STEP(pB0, pB1, pA0, pA1, t, true, true, true);     WAIT_BAR(2); RESC(); ROT();
;     STEP(pA0, pA1, pB0, pB1, t + 1, true, true, true); WAIT_BAR(2); RESC(); ROT();
;   }
;     ...
;   for (; t + 1 < NT; t += 2) {
;     STEP(pB0, pB1, pA0, pA1, t, (t + 3 < NT), (t + 1 < NT), (t + 1 < NT));         ENDW(t);     RESC(); ROT();
;     STEP(pA0, pA1, pB0, pB1, t + 1, (t + 4 < NT), (t + 2 < NT), (t + 2 < NT));     ENDW(t + 1); RESC(); ROT();
	s_add_i32 s14, s17, 0x2000
	s_cmpk_lg_i32 s17, 0x4000
	s_cselect_b32 s14, s14, 0
	v_add_u32_e32 v219, s15, v244
	ds_read_b64_tr_b16 v[222:223], v219 offset:24576
	ds_read_b64_tr_b16 v[224:225], v219 offset:25088
	v_add_f32_e32 v64, v112, v113
	v_add_f32_e32 v64, v114, v64
	v_add_f32_e32 v64, v115, v64
	v_add_f32_e32 v64, v116, v64
	v_add_f32_e32 v64, v117, v64
	v_cvt_pk_bf16_f32 v160, v112, v113
	v_cvt_pk_bf16_f32 v161, v114, v115
	s_waitcnt lgkmcnt(9)
	v_mfma_f32_32x32x16_bf16 v[96:111], v[76:79], v[172:175], v[48:63]
	ds_read_b64_tr_b16 v[112:113], v219 offset:28672
	ds_read_b64_tr_b16 v[114:115], v219 offset:29184
	v_add_f32_e32 v64, v118, v64
	v_add_f32_e32 v64, v119, v64
	v_add_f32_e32 v64, v120, v64
	v_add_f32_e32 v144, v121, v64
	s_waitcnt lgkmcnt(10)
	v_mfma_f32_32x32x16_bf16 v[64:79], v[136:139], v[172:175], v[48:63]
	v_cvt_pk_bf16_f32 v162, v116, v117
	v_cvt_pk_bf16_f32 v163, v118, v119
	ds_read_b64_tr_b16 v[136:137], v219 offset:25600
	ds_read_b64_tr_b16 v[138:139], v219 offset:26112
	v_add_f32_e32 v116, v122, v144
	v_add_f32_e32 v116, v123, v116
	v_add_f32_e32 v116, v124, v116
	v_add_f32_e32 v116, v125, v116
	v_cvt_pk_bf16_f32 v156, v120, v121
	v_cvt_pk_bf16_f32 v157, v122, v123
	s_waitcnt lgkmcnt(11)
	v_mfma_f32_32x32x16_bf16 v[96:111], v[140:143], v[168:171], v[96:111]
	ds_read_b64_tr_b16 v[118:119], v219 offset:29696
	ds_read_b64_tr_b16 v[120:121], v219 offset:30208
	s_waitcnt lgkmcnt(12)
	v_mfma_f32_32x32x16_bf16 v[64:79], v[176:179], v[168:171], v[64:79]
	v_add_f32_e32 v116, v126, v116
	v_add_f32_e32 v116, v127, v116
	v_add_f32_e32 v116, v80, v116
	v_add_f32_e32 v116, v81, v116
	v_cvt_pk_bf16_f32 v158, v124, v125
	v_cvt_pk_bf16_f32 v159, v126, v127
	ds_read_b64_tr_b16 v[122:123], v219 offset:26624
	ds_read_b64_tr_b16 v[124:125], v219 offset:27136
	v_add_f32_e32 v116, v82, v116
	v_add_f32_e32 v116, v83, v116
	v_add_f32_e32 v116, v84, v116
	v_add_f32_e32 v116, v85, v116
	v_cvt_pk_bf16_f32 v148, v80, v81
	v_cvt_pk_bf16_f32 v149, v82, v83
	s_waitcnt lgkmcnt(13)
	v_mfma_f32_32x32x16_bf16 v[96:111], v[180:183], v[164:167], v[96:111]
	ds_read_b64_tr_b16 v[80:81], v219 offset:30720
	ds_read_b64_tr_b16 v[82:83], v219 offset:31232
	s_waitcnt lgkmcnt(14)
	v_mfma_f32_32x32x16_bf16 v[64:79], v[184:187], v[164:167], v[64:79]
	v_add_f32_e32 v116, v86, v116
	v_add_f32_e32 v116, v87, v116
	v_add_f32_e32 v116, v88, v116
	v_add_f32_e32 v116, v89, v116
	v_cvt_pk_bf16_f32 v150, v84, v85
	v_cvt_pk_bf16_f32 v151, v86, v87
	ds_read_b64_tr_b16 v[84:85], v219 offset:27648
	ds_read_b64_tr_b16 v[86:87], v219 offset:28160
	v_add_f32_e32 v116, v90, v116
	v_add_f32_e32 v116, v91, v116
	v_add_f32_e32 v116, v92, v116
	v_add_f32_e32 v116, v93, v116
	v_cvt_pk_bf16_f32 v144, v88, v89
	v_cvt_pk_bf16_f32 v145, v90, v91
	s_waitcnt lgkmcnt(14)
	v_mfma_f32_32x32x16_bf16 v[96:111], v[132:135], v[152:155], v[96:111]
	ds_read_b64_tr_b16 v[88:89], v219 offset:31744
	ds_read_b64_tr_b16 v[90:91], v219 offset:32256
	v_mfma_f32_32x32x16_bf16 v[64:79], v[128:131], v[152:155], v[64:79]
	v_add_f32_e32 v116, v94, v116
	v_add_f32_e32 v116, v95, v116
	v_add_f32_e32 v116, 0, v116
	v_cvt_pk_bf16_f32 v146, v92, v93
	v_cvt_pk_bf16_f32 v147, v94, v95
	s_add_i32 s15, s14, s18
	v_lshl_add_u64 v[92:93], v[220:221], 0, s[94:95]
	s_mov_b32 s18, m0
	s_mov_b32 m0, s15
	s_nop 0
	global_load_lds_dwordx4 v[92:93], off
	s_mov_b32 m0, s18
	v_add_f32_e32 v116, v188, v116
	s_waitcnt lgkmcnt(14)
	v_mfma_f32_32x32x16_bf16 v[16:31], v[160:163], v[222:225], v[16:31]
	v_exp_f32_e32 v96, v96
	v_exp_f32_e32 v97, v97
	v_exp_f32_e32 v98, v98
	v_exp_f32_e32 v99, v99
	s_waitcnt lgkmcnt(12)
	v_mfma_f32_32x32x16_bf16 v[32:47], v[160:163], v[112:115], v[32:47]
	v_exp_f32_e32 v100, v100
	v_exp_f32_e32 v101, v101
	v_exp_f32_e32 v102, v102
	v_exp_f32_e32 v103, v103
	v_add_u32_e32 v92, s14, v242
	ds_read_b128 v[126:129], v92
	ds_read_b128 v[130:133], v92 offset:512
	s_waitcnt lgkmcnt(12)
	v_mfma_f32_32x32x16_bf16 v[16:31], v[156:159], v[136:139], v[16:31]
	v_exp_f32_e32 v104, v104
	v_exp_f32_e32 v105, v105
	v_exp_f32_e32 v106, v106
	v_exp_f32_e32 v107, v107
	ds_read_b128 v[134:137], v92 offset:2048
	ds_read_b128 v[138:141], v92 offset:2560
	s_waitcnt lgkmcnt(12)
	v_mfma_f32_32x32x16_bf16 v[32:47], v[156:159], v[118:121], v[32:47]
	v_exp_f32_e32 v108, v108
	v_exp_f32_e32 v109, v109
	v_exp_f32_e32 v110, v110
	v_exp_f32_e32 v111, v111
	ds_read_b128 v[118:121], v92 offset:4096
	ds_read_b128 v[176:179], v92 offset:4608
	s_waitcnt lgkmcnt(12)
	v_mfma_f32_32x32x16_bf16 v[16:31], v[148:151], v[122:125], v[16:31]
	v_exp_f32_e32 v64, v64
	v_exp_f32_e32 v65, v65
	v_exp_f32_e32 v66, v66
	v_exp_f32_e32 v67, v67
	ds_read_b128 v[122:125], v92 offset:6144
	ds_read_b128 v[112:115], v92 offset:6656
	s_waitcnt lgkmcnt(12)
	v_mfma_f32_32x32x16_bf16 v[32:47], v[148:151], v[80:83], v[32:47]
	v_exp_f32_e32 v68, v68
	v_exp_f32_e32 v69, v69
	v_exp_f32_e32 v70, v70
	v_exp_f32_e32 v71, v71
	s_waitcnt lgkmcnt(10)
	v_mfma_f32_32x32x16_bf16 v[16:31], v[144:147], v[84:87], v[16:31]
	v_exp_f32_e32 v72, v72
	v_exp_f32_e32 v73, v73
	v_exp_f32_e32 v74, v74
	v_exp_f32_e32 v75, v75
	s_waitcnt lgkmcnt(8)
	v_mfma_f32_32x32x16_bf16 v[32:47], v[144:147], v[88:91], v[32:47]
	v_exp_f32_e32 v76, v76
	v_exp_f32_e32 v77, v77
	v_exp_f32_e32 v78, v78
	v_exp_f32_e32 v79, v79
	s_waitcnt vmcnt(0) lgkmcnt(0)
	s_barrier
; #define WAIT_BAR(N) asm volatile("s_waitcnt vmcnt(" #N ") lgkmcnt(0)\n\ts_barrier" ::: "memory")
;   #define RESC() do { } while (0)
;   #define ROT() do { sl_prev = sl_cur; sl_cur = sl_next; sl_next = (sl_next == (NSLOT - 1) * SLOTB) ? 0 : sl_next + SLOTB; } while (0)
;   #define ENDW(tt) do { if ((tt) + 3 < NT) { WAIT_BAR(2); } else if ((tt) + 2 < NT) { WAIT_BAR(1); } else { WAIT_BAR(0); } } while (0)
; template <int THRL> __device__ __forceinline__ void attn_unit(const int tid, const float mfix, int q0, int NT, const bf16* Qh, const bf16* __restrict__ Kh, const bf16* __restrict__ Vh, const bf16* Zh, bf16* Oh, const long PQ, const long PO, char* shm) {
;     ...
;   int t = 1;
;   for (; t + 5 < NT; t += 2) {
;     STEP(pB0, pB1, pA0, pA1, t, true, true, true);     WAIT_BAR(2); RESC(); ROT();
;     STEP(pA0, pA1, pB0, pB1, t + 1, true, true, true); WAIT_BAR(2); RESC(); ROT();
;   }
;     ...
;   for (; t + 1 < NT; t += 2) {
;     STEP(pB0, pB1, pA0, pA1, t, (t + 3 < NT), (t + 1 < NT), (t + 1 < NT));         ENDW(t);     RESC(); ROT();
;     STEP(pA0, pA1, pB0, pB1, t + 1, (t + 4 < NT), (t + 2 < NT), (t + 2 < NT));     ENDW(t + 1); RESC(); ROT();
;   }
;   STEP(pB0, pB1, pA0, pA1, NT - 1, false, false, false); RESC();
	v_add_u32_e32 v117, s17, v244
	ds_read_b64_tr_b16 v[180:181], v117 offset:24576
	ds_read_b64_tr_b16 v[182:183], v117 offset:25088
	v_add_f32_e32 v80, v96, v97
	v_add_f32_e32 v80, v98, v80
	v_add_f32_e32 v80, v99, v80
	v_add_f32_e32 v80, v100, v80
	v_add_f32_e32 v142, v101, v80
	v_cvt_pk_bf16_f32 v160, v96, v97
	v_cvt_pk_bf16_f32 v161, v98, v99
	s_waitcnt lgkmcnt(9)
	v_mfma_f32_32x32x16_bf16 v[80:95], v[126:129], v[172:175], v[48:63]
	ds_read_b64_tr_b16 v[96:97], v117 offset:28672
	ds_read_b64_tr_b16 v[98:99], v117 offset:29184
	s_waitcnt lgkmcnt(10)
	v_mfma_f32_32x32x16_bf16 v[48:63], v[130:133], v[172:175], v[48:63]
	v_add_f32_e32 v126, v102, v142
	v_add_f32_e32 v126, v103, v126
	v_add_f32_e32 v126, v104, v126
	v_add_f32_e32 v126, v105, v126
	v_cvt_pk_bf16_f32 v162, v100, v101
	v_cvt_pk_bf16_f32 v163, v102, v103
	ds_read_b64_tr_b16 v[100:101], v117 offset:25600
	ds_read_b64_tr_b16 v[102:103], v117 offset:26112
	v_add_f32_e32 v126, v106, v126
	v_add_f32_e32 v126, v107, v126
	v_add_f32_e32 v126, v108, v126
	v_add_f32_e32 v126, v109, v126
	v_cvt_pk_bf16_f32 v156, v104, v105
	v_cvt_pk_bf16_f32 v157, v106, v107
	s_waitcnt lgkmcnt(11)
	v_mfma_f32_32x32x16_bf16 v[80:95], v[134:137], v[168:171], v[80:95]
	ds_read_b64_tr_b16 v[104:105], v117 offset:29696
	ds_read_b64_tr_b16 v[106:107], v117 offset:30208
	s_waitcnt lgkmcnt(12)
	v_mfma_f32_32x32x16_bf16 v[48:63], v[138:141], v[168:171], v[48:63]
	v_add_f32_e32 v126, v110, v126
	v_add_f32_e32 v126, v111, v126
	v_add_f32_e32 v126, v64, v126
	v_add_f32_e32 v126, v65, v126
	v_cvt_pk_bf16_f32 v158, v108, v109
	v_cvt_pk_bf16_f32 v159, v110, v111
	ds_read_b64_tr_b16 v[108:109], v117 offset:26624
	ds_read_b64_tr_b16 v[110:111], v117 offset:27136
	s_waitcnt lgkmcnt(13)
	v_mfma_f32_32x32x16_bf16 v[80:95], v[118:121], v[164:167], v[80:95]
	v_add_f32_e32 v118, v66, v126
	v_add_f32_e32 v118, v67, v118
	v_add_f32_e32 v118, v68, v118
	v_add_f32_e32 v118, v69, v118
	v_cvt_pk_bf16_f32 v148, v64, v65
	v_cvt_pk_bf16_f32 v149, v66, v67
	ds_read_b64_tr_b16 v[64:65], v117 offset:30720
	ds_read_b64_tr_b16 v[66:67], v117 offset:31232
	s_waitcnt lgkmcnt(14)
	v_mfma_f32_32x32x16_bf16 v[48:63], v[176:179], v[164:167], v[48:63]
	v_add_f32_e32 v118, v70, v118
	v_add_f32_e32 v118, v71, v118
	v_add_f32_e32 v118, v72, v118
	v_add_f32_e32 v118, v73, v118
	v_cvt_pk_bf16_f32 v150, v68, v69
	v_cvt_pk_bf16_f32 v151, v70, v71
	ds_read_b64_tr_b16 v[68:69], v117 offset:27648
	ds_read_b64_tr_b16 v[70:71], v117 offset:28160
	v_add_f32_e32 v118, v74, v118
	v_add_f32_e32 v118, v75, v118
	v_add_f32_e32 v118, v76, v118
	v_add_f32_e32 v118, v77, v118
	v_cvt_pk_bf16_f32 v144, v72, v73
	v_cvt_pk_bf16_f32 v145, v74, v75
	s_waitcnt lgkmcnt(14)
	v_mfma_f32_32x32x16_bf16 v[80:95], v[122:125], v[152:155], v[80:95]
	ds_read_b64_tr_b16 v[72:73], v117 offset:31744
	ds_read_b64_tr_b16 v[74:75], v117 offset:32256
	v_mfma_f32_32x32x16_bf16 v[48:63], v[112:115], v[152:155], v[48:63]
	v_add_f32_e32 v112, v78, v118
	v_add_f32_e32 v112, v79, v112
	v_add_f32_e32 v112, 0, v112
	v_cvt_pk_bf16_f32 v146, v76, v77
	v_cvt_pk_bf16_f32 v147, v78, v79
	s_waitcnt lgkmcnt(14)
	v_mfma_f32_32x32x16_bf16 v[16:31], v[160:163], v[180:183], v[16:31]
	s_nop 1
	v_exp_f32_e32 v80, v80
	v_exp_f32_e32 v81, v81
	v_exp_f32_e32 v82, v82
	v_exp_f32_e32 v83, v83
	s_waitcnt lgkmcnt(12)
	v_mfma_f32_32x32x16_bf16 v[32:47], v[160:163], v[96:99], v[32:47]
	v_exp_f32_e32 v84, v84
	v_exp_f32_e32 v85, v85
	v_exp_f32_e32 v86, v86
	v_exp_f32_e32 v87, v87
	s_waitcnt lgkmcnt(10)
	v_mfma_f32_32x32x16_bf16 v[16:31], v[156:159], v[100:103], v[16:31]
	v_exp_f32_e32 v88, v88
	v_exp_f32_e32 v89, v89
	v_exp_f32_e32 v90, v90
	v_exp_f32_e32 v91, v91
	s_waitcnt lgkmcnt(8)
	v_mfma_f32_32x32x16_bf16 v[32:47], v[156:159], v[104:107], v[32:47]
	v_exp_f32_e32 v92, v92
	v_exp_f32_e32 v93, v93
	v_exp_f32_e32 v94, v94
	v_exp_f32_e32 v95, v95
	s_waitcnt lgkmcnt(6)
; #define SBAR() __builtin_amdgcn_sched_barrier(0)
; #define WAIT_BAR(N) asm volatile("s_waitcnt vmcnt(" #N ") lgkmcnt(0)\n\ts_barrier" ::: "memory")
;   #define RESC() do { } while (0)
;   #define ROT() do { sl_prev = sl_cur; sl_cur = sl_next; sl_next = (sl_next == (NSLOT - 1) * SLOTB) ? 0 : sl_next + SLOTB; } while (0)
;   #define PKW(P, B) cvtpk_s(P[B], P[B + 1])
;   #define ENDW(tt) do { if ((tt) + 3 < NT) { WAIT_BAR(2); } else if ((tt) + 2 < NT) { WAIT_BAR(1); } else { WAIT_BAR(0); } } while (0)
; template <int THRL> __device__ __forceinline__ void attn_unit(const int tid, const float mfix, int q0, int NT, const bf16* Qh, const bf16* __restrict__ Kh, const bf16* __restrict__ Vh, const bf16* Zh, bf16* Oh, const long PQ, const long PO, char* shm) {
;     ...
;   int t = 1;
;   for (; t + 5 < NT; t += 2) {
;     STEP(pB0, pB1, pA0, pA1, t, true, true, true);     WAIT_BAR(2); RESC(); ROT();
;     STEP(pA0, pA1, pB0, pB1, t + 1, true, true, true); WAIT_BAR(2); RESC(); ROT();
;   }
;     ...
;   for (; t + 1 < NT; t += 2) {
;     STEP(pB0, pB1, pA0, pA1, t, (t + 3 < NT), (t + 1 < NT), (t + 1 < NT));         ENDW(t);     RESC(); ROT();
;     STEP(pA0, pA1, pB0, pB1, t + 1, (t + 4 < NT), (t + 2 < NT), (t + 2 < NT));     ENDW(t + 1); RESC(); ROT();
;   }
;   STEP(pB0, pB1, pA0, pA1, NT - 1, false, false, false); RESC();
;   { float sacc = pB0[0] + pB0[1]; _Pragma("unroll") for (int r = 2; r < 16; ++r) sacc += pB0[r]; _Pragma("unroll") for (int r = 0; r < 16; ++r) sacc += pB1[r]; l_reg += sacc;
;     pw0 = (u32x4){PKW(pB0, 0), PKW(pB0, 2), PKW(pB0, 4), PKW(pB0, 6)}; pw1 = (u32x4){PKW(pB0, 8), PKW(pB0, 10), PKW(pB0, 12), PKW(pB0, 14)}; pw2 = (u32x4){PKW(pB1, 0), PKW(pB1, 2), PKW(pB1, 4), PKW(pB1, 6)}; pw3 = (u32x4){PKW(pB1, 8), PKW(pB1, 10), PKW(pB1, 12), PKW(pB1, 14)};
;     SBAR(); pv(o, vb0 + sl_cur, PAF(0), PAF(1), PAF(2), PAF(3)); }
;     ...
;   { auto rr = __builtin_amdgcn_permlane32_swap(__float_as_uint(l_reg), __float_as_uint(l_reg), false, false); l_reg = __uint_as_float(rr[0]) + __uint_as_float(rr[1]); }
;   if (hi == 0) wsf[32 + r32] = l_reg; asm volatile("s_waitcnt lgkmcnt(0)" ::: "memory");
	v_mfma_f32_32x32x16_bf16 v[16:31], v[148:151], v[108:111], v[16:31]
	v_exp_f32_e32 v48, v48
	v_exp_f32_e32 v49, v49
	v_exp_f32_e32 v50, v50
	v_exp_f32_e32 v51, v51
	s_waitcnt lgkmcnt(4)
	v_mfma_f32_32x32x16_bf16 v[32:47], v[148:151], v[64:67], v[32:47]
	v_exp_f32_e32 v52, v52
	v_exp_f32_e32 v53, v53
	v_exp_f32_e32 v54, v54
	v_exp_f32_e32 v55, v55
	s_waitcnt lgkmcnt(2)
	v_mfma_f32_32x32x16_bf16 v[16:31], v[144:147], v[68:71], v[16:31]
	v_exp_f32_e32 v56, v56
	v_exp_f32_e32 v57, v57
	v_exp_f32_e32 v58, v58
	v_exp_f32_e32 v59, v59
	s_waitcnt lgkmcnt(0)
	v_mfma_f32_32x32x16_bf16 v[32:47], v[144:147], v[72:75], v[32:47]
	v_exp_f32_e32 v60, v60
	v_exp_f32_e32 v61, v61
	v_exp_f32_e32 v62, v62
	v_exp_f32_e32 v63, v63
	v_add_f32_e32 v64, v80, v81
	v_add_f32_e32 v64, v82, v64
	v_add_f32_e32 v64, v83, v64
	v_add_f32_e32 v64, v84, v64
	v_add_f32_e32 v64, v85, v64
	v_add_f32_e32 v64, v86, v64
	v_add_f32_e32 v64, v87, v64
	v_add_f32_e32 v64, v88, v64
	v_add_f32_e32 v64, v89, v64
	v_add_f32_e32 v64, v90, v64
	v_add_f32_e32 v64, v91, v64
	v_add_f32_e32 v64, v92, v64
	v_add_f32_e32 v64, v93, v64
	v_add_f32_e32 v64, v94, v64
	v_add_f32_e32 v64, v95, v64
	v_add_f32_e32 v64, v48, v64
	v_add_f32_e32 v64, v49, v64
	v_add_f32_e32 v64, v50, v64
	v_add_f32_e32 v64, v51, v64
	v_add_f32_e32 v64, v52, v64
	v_add_f32_e32 v64, v53, v64
	v_add_f32_e32 v64, v54, v64
	v_add_f32_e32 v64, v55, v64
	v_add_f32_e32 v64, v56, v64
	v_add_f32_e32 v64, v57, v64
	v_add_f32_e32 v64, v58, v64
	v_add_f32_e32 v64, v59, v64
	v_add_f32_e32 v64, v60, v64
	v_add_f32_e32 v64, v61, v64
	v_add_f32_e32 v64, v62, v64
	v_add_f32_e32 v64, v63, v64
	v_add_f32_e32 v65, v116, v112
	v_add_f32_e32 v64, v65, v64
	v_cvt_pk_bf16_f32 v48, v48, v49
	v_cvt_pk_bf16_f32 v66, v80, v81
	v_cvt_pk_bf16_f32 v67, v82, v83
	v_cvt_pk_bf16_f32 v68, v84, v85
	v_cvt_pk_bf16_f32 v69, v86, v87
	v_cvt_pk_bf16_f32 v70, v88, v89
	v_cvt_pk_bf16_f32 v71, v90, v91
	v_cvt_pk_bf16_f32 v72, v92, v93
	v_cvt_pk_bf16_f32 v73, v94, v95
	v_cvt_pk_bf16_f32 v49, v50, v51
	v_cvt_pk_bf16_f32 v50, v52, v53
	v_cvt_pk_bf16_f32 v51, v54, v55
	v_cvt_pk_bf16_f32 v52, v56, v57
	v_cvt_pk_bf16_f32 v53, v58, v59
	v_cvt_pk_bf16_f32 v54, v60, v61
	v_cvt_pk_bf16_f32 v55, v62, v63
	v_add_u32_e32 v65, s14, v243
	ds_read_b64_tr_b16 v[56:57],v65 offset:0
	ds_read_b64_tr_b16 v[58:59],v65 offset:512
	ds_read_b64_tr_b16 v[60:61],v65 offset:1024
	ds_read_b64_tr_b16 v[62:63],v65 offset:1536
	ds_read_b64_tr_b16 v[74:75],v65 offset:2048
	ds_read_b64_tr_b16 v[76:77],v65 offset:2560
	ds_read_b64_tr_b16 v[78:79],v65 offset:3072
	ds_read_b64_tr_b16 v[80:81],v65 offset:3584
	s_waitcnt lgkmcnt(0)
	s_nop 0
	v_mfma_f32_32x32x16_bf16 v[16:31], v[66:69], v[56:59], v[16:31]
	ds_read_b64_tr_b16 v[56:57],v65 offset:4096
	ds_read_b64_tr_b16 v[58:59],v65 offset:4608
	v_mfma_f32_32x32x16_bf16 v[16:31], v[70:73], v[60:63], v[16:31]
	ds_read_b64_tr_b16 v[60:61],v65 offset:5120
	ds_read_b64_tr_b16 v[62:63],v65 offset:5632
	v_mfma_f32_32x32x16_bf16 v[16:31], v[48:51], v[74:77], v[16:31]
	ds_read_b64_tr_b16 v[74:75],v65 offset:6144
	ds_read_b64_tr_b16 v[76:77],v65 offset:6656
	v_mfma_f32_32x32x16_bf16 v[16:31], v[52:55], v[78:81], v[16:31]
	ds_read_b64_tr_b16 v[78:79],v65 offset:7168
	ds_read_b64_tr_b16 v[80:81],v65 offset:7680
	s_waitcnt lgkmcnt(0)
	v_mfma_f32_32x32x16_bf16 v[32:47], v[66:69], v[56:59], v[32:47]
	v_mfma_f32_32x32x16_bf16 v[32:47], v[70:73], v[60:63], v[32:47]
	v_mfma_f32_32x32x16_bf16 v[32:47], v[48:51], v[74:77], v[32:47]
	v_mov_b32_e32 v48, v64
	s_nop 1
	v_permlane32_swap_b32_e32 v64, v48
	v_mfma_f32_32x32x16_bf16 v[32:47], v[52:55], v[78:81], v[32:47]
	s_and_saveexec_b64 s[14:15], s[4:5]
	s_cbranch_execz .LBB0_386
	v_add_f32_e32 v48, v64, v48
	v_lshl_add_u32 v49, v239, 2, s16
	ds_write_b32 v49, v48 offset:49280
	s_branch .LBB0_386
